# K-loops: the s_waitcnt lgkmcnt(0) repeated right after the barrier at the head of every MFMA block removed (the identical wait in front of the barrier already covers it)
# speedup vs baseline: 1.0009x; 1.0006x over previous
.LBB0_98:
	s_add_u32 s18, s44, 0xfffc0080
	s_addc_u32 s19, s45, -1
	s_add_i32 s46, 0, 0x10000
	s_cmp_eq_u32 s15, 12
	s_cselect_b32 s25, s7, s19
	s_cselect_b32 s24, s10, s18
	s_cselect_b32 s23, s5, s14
	s_cselect_b32 s22, s11, s13
	s_add_i32 s47, 0, 0x14000
	ds_read_b128 v[156:159], v240
	ds_read_b128 v[160:163], v240 offset:1024
	ds_read_b128 v[164:167], v240 offset:2048
	ds_read_b128 v[168:171], v240 offset:3072
	ds_read_b128 v[172:175], v240 offset:16384
	ds_read_b128 v[176:179], v240 offset:17408
	ds_read_b128 v[180:183], v240 offset:18432
	ds_read_b128 v[184:187], v240 offset:19456
	s_add_i32 m0, s29, 0xc000
	ds_read_b128 v[208:211], v155
	ds_read_b128 v[212:215], v155 offset:1024
	ds_read_b128 v[216:219], v155 offset:2048
	ds_read_b128 v[220:223], v155 offset:3072
	ds_read_b128 v[224:227], v155 offset:4096
	ds_read_b128 v[228:231], v155 offset:5120
	ds_read_b128 v[232:235], v155 offset:6144
	ds_read_b128 v[236:239], v155 offset:7168
	global_load_lds_dwordx4 v144, s[44:45]
	s_add_i32 m0, s29, 0xe000
	s_nop 0
	global_load_lds_dwordx4 v146, s[44:45]
	s_waitcnt vmcnt(8)
	s_waitcnt lgkmcnt(0)
	s_barrier
	s_setprio 1
	v_mfma_f32_16x16x32_bf16 v[128:131], v[156:159], v[208:211], v[128:131]
	v_mfma_f32_16x16x32_bf16 v[120:123], v[164:167], v[208:211], v[120:123]
	v_mfma_f32_16x16x32_bf16 v[112:115], v[156:159], v[216:219], v[112:115]
	v_mfma_f32_16x16x32_bf16 v[104:107], v[164:167], v[216:219], v[104:107]
	v_mfma_f32_16x16x32_bf16 v[96:99], v[156:159], v[224:227], v[96:99]
	v_mfma_f32_16x16x32_bf16 v[88:91], v[164:167], v[224:227], v[88:91]
	v_mfma_f32_16x16x32_bf16 v[80:83], v[156:159], v[232:235], v[80:83]
	v_mfma_f32_16x16x32_bf16 v[72:75], v[164:167], v[232:235], v[72:75]
	v_mfma_f32_16x16x32_bf16 v[128:131], v[160:163], v[212:215], v[128:131]
	v_mfma_f32_16x16x32_bf16 v[120:123], v[168:171], v[212:215], v[120:123]
	v_mfma_f32_16x16x32_bf16 v[112:115], v[160:163], v[220:223], v[112:115]
	v_mfma_f32_16x16x32_bf16 v[104:107], v[168:171], v[220:223], v[104:107]
	v_mfma_f32_16x16x32_bf16 v[96:99], v[160:163], v[228:231], v[96:99]
	v_mfma_f32_16x16x32_bf16 v[88:91], v[168:171], v[228:231], v[88:91]
	v_mfma_f32_16x16x32_bf16 v[80:83], v[160:163], v[236:239], v[80:83]
	v_mfma_f32_16x16x32_bf16 v[72:75], v[168:171], v[236:239], v[72:75]
	s_setprio 0
	s_setprio 1
	v_mfma_f32_16x16x32_bf16 v[124:127], v[172:175], v[208:211], v[124:127]
	v_mfma_f32_16x16x32_bf16 v[116:119], v[180:183], v[208:211], v[116:119]
	v_mfma_f32_16x16x32_bf16 v[108:111], v[172:175], v[216:219], v[108:111]
	v_mfma_f32_16x16x32_bf16 v[100:103], v[180:183], v[216:219], v[100:103]
	v_mfma_f32_16x16x32_bf16 v[92:95], v[172:175], v[224:227], v[92:95]
	v_mfma_f32_16x16x32_bf16 v[84:87], v[180:183], v[224:227], v[84:87]
	v_mfma_f32_16x16x32_bf16 v[76:79], v[172:175], v[232:235], v[76:79]
	v_mfma_f32_16x16x32_bf16 v[68:71], v[180:183], v[232:235], v[68:71]
	v_mfma_f32_16x16x32_bf16 v[124:127], v[176:179], v[212:215], v[124:127]
	v_mfma_f32_16x16x32_bf16 v[116:119], v[184:187], v[212:215], v[116:119]
	v_mfma_f32_16x16x32_bf16 v[108:111], v[176:179], v[220:223], v[108:111]
	v_mfma_f32_16x16x32_bf16 v[100:103], v[184:187], v[220:223], v[100:103]
	v_mfma_f32_16x16x32_bf16 v[92:95], v[176:179], v[228:231], v[92:95]
	v_mfma_f32_16x16x32_bf16 v[84:87], v[184:187], v[228:231], v[84:87]
	v_mfma_f32_16x16x32_bf16 v[76:79], v[176:179], v[236:239], v[76:79]
	v_mfma_f32_16x16x32_bf16 v[68:71], v[184:187], v[236:239], v[68:71]
	s_setprio 0
	s_barrier
	s_add_i32 s18, s46, s28
	s_mov_b32 m0, s18
	ds_read_b128 v[208:211], v155 offset:16384
	ds_read_b128 v[212:215], v155 offset:17408
	ds_read_b128 v[216:219], v155 offset:18432
	ds_read_b128 v[220:223], v155 offset:19456
	ds_read_b128 v[224:227], v155 offset:20480
	ds_read_b128 v[228:231], v155 offset:21504
	ds_read_b128 v[232:235], v155 offset:22528
	ds_read_b128 v[236:239], v155 offset:23552
	global_load_lds_dwordx4 v2, s[22:23]
	s_add_i32 m0, s18, 0x2000
	s_add_u32 s18, s22, 0x40000
	s_addc_u32 s19, s23, 0
	s_add_i32 s46, s47, s28
	global_load_lds_dwordx4 v142, s[22:23]
	s_mov_b32 m0, s46
	s_nop 0
	global_load_lds_dwordx4 v2, s[18:19]
	s_add_i32 m0, s46, 0x2000
	s_nop 0
	global_load_lds_dwordx4 v142, s[18:19]
	s_mov_b32 m0, s29
	s_nop 0
	global_load_lds_dwordx4 v0, s[24:25]
	s_mov_b32 m0, s43
	s_nop 0
	global_load_lds_dwordx4 v140, s[24:25]
	s_waitcnt vmcnt(8)
	s_waitcnt lgkmcnt(0)
	s_barrier
	s_setprio 1
	v_mfma_f32_16x16x32_bf16 v[64:67], v[156:159], v[208:211], v[64:67]
	v_mfma_f32_16x16x32_bf16 v[56:59], v[164:167], v[208:211], v[56:59]
	v_mfma_f32_16x16x32_bf16 v[48:51], v[156:159], v[216:219], v[48:51]
	v_mfma_f32_16x16x32_bf16 v[40:43], v[164:167], v[216:219], v[40:43]
	v_mfma_f32_16x16x32_bf16 v[32:35], v[156:159], v[224:227], v[32:35]
	v_mfma_f32_16x16x32_bf16 v[24:27], v[164:167], v[224:227], v[24:27]
	v_mfma_f32_16x16x32_bf16 v[16:19], v[156:159], v[232:235], v[16:19]
	v_mfma_f32_16x16x32_bf16 v[8:11], v[164:167], v[232:235], v[8:11]
	v_mfma_f32_16x16x32_bf16 v[64:67], v[160:163], v[212:215], v[64:67]
	v_mfma_f32_16x16x32_bf16 v[56:59], v[168:171], v[212:215], v[56:59]
	v_mfma_f32_16x16x32_bf16 v[48:51], v[160:163], v[220:223], v[48:51]
	v_mfma_f32_16x16x32_bf16 v[40:43], v[168:171], v[220:223], v[40:43]
	v_mfma_f32_16x16x32_bf16 v[32:35], v[160:163], v[228:231], v[32:35]
	v_mfma_f32_16x16x32_bf16 v[24:27], v[168:171], v[228:231], v[24:27]
	v_mfma_f32_16x16x32_bf16 v[16:19], v[160:163], v[236:239], v[16:19]
	v_mfma_f32_16x16x32_bf16 v[8:11], v[168:171], v[236:239], v[8:11]
	s_setprio 0
	s_setprio 1
	v_mfma_f32_16x16x32_bf16 v[60:63], v[172:175], v[208:211], v[60:63]
	v_mfma_f32_16x16x32_bf16 v[52:55], v[180:183], v[208:211], v[52:55]
	v_mfma_f32_16x16x32_bf16 v[44:47], v[172:175], v[216:219], v[44:47]
	v_mfma_f32_16x16x32_bf16 v[36:39], v[180:183], v[216:219], v[36:39]
	v_mfma_f32_16x16x32_bf16 v[28:31], v[172:175], v[224:227], v[28:31]
	v_mfma_f32_16x16x32_bf16 v[20:23], v[180:183], v[224:227], v[20:23]
	v_mfma_f32_16x16x32_bf16 v[12:15], v[172:175], v[232:235], v[12:15]
	v_mfma_f32_16x16x32_bf16 v[4:7], v[180:183], v[232:235], v[4:7]
	v_mfma_f32_16x16x32_bf16 v[60:63], v[176:179], v[212:215], v[60:63]
	v_mfma_f32_16x16x32_bf16 v[52:55], v[184:187], v[212:215], v[52:55]
	v_mfma_f32_16x16x32_bf16 v[44:47], v[176:179], v[220:223], v[44:47]
	v_mfma_f32_16x16x32_bf16 v[36:39], v[184:187], v[220:223], v[36:39]
	v_mfma_f32_16x16x32_bf16 v[28:31], v[176:179], v[228:231], v[28:31]
	v_mfma_f32_16x16x32_bf16 v[20:23], v[184:187], v[228:231], v[20:23]
	v_mfma_f32_16x16x32_bf16 v[12:15], v[176:179], v[236:239], v[12:15]
	v_mfma_f32_16x16x32_bf16 v[4:7], v[184:187], v[236:239], v[4:7]
	s_setprio 0
	s_barrier
	s_add_i32 s46, 0, 0x18000
	s_add_i32 s47, 0, 0x1c000
	ds_read_b128 v[156:159], v240 offset:32768
	ds_read_b128 v[160:163], v240 offset:33792
	ds_read_b128 v[164:167], v240 offset:34816
	ds_read_b128 v[168:171], v240 offset:35840
	ds_read_b128 v[172:175], v240 offset:49152
	ds_read_b128 v[176:179], v240 offset:50176
	ds_read_b128 v[180:183], v240 offset:51200
	ds_read_b128 v[184:187], v240 offset:52224
	s_add_u32 s18, s24, 0x40000
	s_addc_u32 s19, s25, 0
	s_mov_b32 m0, s48
	ds_read_b128 v[208:211], v155 offset:32768
	ds_read_b128 v[212:215], v155 offset:33792
	ds_read_b128 v[216:219], v155 offset:34816
	ds_read_b128 v[220:223], v155 offset:35840
	ds_read_b128 v[224:227], v155 offset:36864
	ds_read_b128 v[228:231], v155 offset:37888
	ds_read_b128 v[232:235], v155 offset:38912
	ds_read_b128 v[236:239], v155 offset:39936
	global_load_lds_dwordx4 v0, s[18:19]
	s_mov_b32 m0, s49
	s_nop 0
	global_load_lds_dwordx4 v140, s[18:19]
	s_waitcnt vmcnt(8)
	s_waitcnt lgkmcnt(0)
	s_barrier
	s_setprio 1
	v_mfma_f32_16x16x32_bf16 v[128:131], v[156:159], v[208:211], v[128:131]
	v_mfma_f32_16x16x32_bf16 v[120:123], v[164:167], v[208:211], v[120:123]
	v_mfma_f32_16x16x32_bf16 v[112:115], v[156:159], v[216:219], v[112:115]
	v_mfma_f32_16x16x32_bf16 v[104:107], v[164:167], v[216:219], v[104:107]
	v_mfma_f32_16x16x32_bf16 v[96:99], v[156:159], v[224:227], v[96:99]
	v_mfma_f32_16x16x32_bf16 v[88:91], v[164:167], v[224:227], v[88:91]
	v_mfma_f32_16x16x32_bf16 v[80:83], v[156:159], v[232:235], v[80:83]
	v_mfma_f32_16x16x32_bf16 v[72:75], v[164:167], v[232:235], v[72:75]
	v_mfma_f32_16x16x32_bf16 v[128:131], v[160:163], v[212:215], v[128:131]
	v_mfma_f32_16x16x32_bf16 v[120:123], v[168:171], v[212:215], v[120:123]
	v_mfma_f32_16x16x32_bf16 v[112:115], v[160:163], v[220:223], v[112:115]
	v_mfma_f32_16x16x32_bf16 v[104:107], v[168:171], v[220:223], v[104:107]
	v_mfma_f32_16x16x32_bf16 v[96:99], v[160:163], v[228:231], v[96:99]
	v_mfma_f32_16x16x32_bf16 v[88:91], v[168:171], v[228:231], v[88:91]
	v_mfma_f32_16x16x32_bf16 v[80:83], v[160:163], v[236:239], v[80:83]
	v_mfma_f32_16x16x32_bf16 v[72:75], v[168:171], v[236:239], v[72:75]
	s_setprio 0
	s_setprio 1
	v_mfma_f32_16x16x32_bf16 v[124:127], v[172:175], v[208:211], v[124:127]
	v_mfma_f32_16x16x32_bf16 v[116:119], v[180:183], v[208:211], v[116:119]
	v_mfma_f32_16x16x32_bf16 v[108:111], v[172:175], v[216:219], v[108:111]
	v_mfma_f32_16x16x32_bf16 v[100:103], v[180:183], v[216:219], v[100:103]
	v_mfma_f32_16x16x32_bf16 v[92:95], v[172:175], v[224:227], v[92:95]
	v_mfma_f32_16x16x32_bf16 v[84:87], v[180:183], v[224:227], v[84:87]
	v_mfma_f32_16x16x32_bf16 v[76:79], v[172:175], v[232:235], v[76:79]
	v_mfma_f32_16x16x32_bf16 v[68:71], v[180:183], v[232:235], v[68:71]
	v_mfma_f32_16x16x32_bf16 v[124:127], v[176:179], v[212:215], v[124:127]
	v_mfma_f32_16x16x32_bf16 v[116:119], v[184:187], v[212:215], v[116:119]
	v_mfma_f32_16x16x32_bf16 v[108:111], v[176:179], v[220:223], v[108:111]
	v_mfma_f32_16x16x32_bf16 v[100:103], v[184:187], v[220:223], v[100:103]
	v_mfma_f32_16x16x32_bf16 v[92:95], v[176:179], v[228:231], v[92:95]
	v_mfma_f32_16x16x32_bf16 v[84:87], v[184:187], v[228:231], v[84:87]
	v_mfma_f32_16x16x32_bf16 v[76:79], v[176:179], v[236:239], v[76:79]
	v_mfma_f32_16x16x32_bf16 v[68:71], v[184:187], v[236:239], v[68:71]
	s_setprio 0
	s_barrier
	s_add_i32 s18, s46, s28
	s_add_u32 s100, s22, 0x80
	s_addc_u32 s101, s23, 0
	s_mov_b32 m0, s18
	ds_read_b128 v[208:211], v155 offset:49152
	ds_read_b128 v[212:215], v155 offset:50176
	ds_read_b128 v[216:219], v155 offset:51200
	ds_read_b128 v[220:223], v155 offset:52224
	ds_read_b128 v[224:227], v155 offset:53248
	ds_read_b128 v[228:231], v155 offset:54272
	ds_read_b128 v[232:235], v155 offset:55296
	ds_read_b128 v[236:239], v155 offset:56320
	global_load_lds_dwordx4 v2, s[100:101]
	s_add_i32 m0, s18, 0x2000
	s_add_u32 s18, s22, 0x40080
	s_addc_u32 s19, s23, 0
	s_add_i32 s22, s47, s28
	global_load_lds_dwordx4 v142, s[100:101]
	s_mov_b32 m0, s22
	s_nop 0
	global_load_lds_dwordx4 v2, s[18:19]
	s_add_i32 m0, s22, 0x2000
	s_nop 0
	global_load_lds_dwordx4 v142, s[18:19]
	s_add_u32 s100, s24, 0x80
	s_addc_u32 s101, s25, 0
	s_mov_b32 m0, s50
	s_nop 0
	global_load_lds_dwordx4 v0, s[100:101]
	s_mov_b32 m0, s51
	s_nop 0
	global_load_lds_dwordx4 v140, s[100:101]
	s_waitcnt vmcnt(8)
	s_waitcnt lgkmcnt(0)
	s_barrier
	s_setprio 1
	v_mfma_f32_16x16x32_bf16 v[64:67], v[156:159], v[208:211], v[64:67]
	v_mfma_f32_16x16x32_bf16 v[56:59], v[164:167], v[208:211], v[56:59]
	v_mfma_f32_16x16x32_bf16 v[48:51], v[156:159], v[216:219], v[48:51]
	v_mfma_f32_16x16x32_bf16 v[40:43], v[164:167], v[216:219], v[40:43]
	v_mfma_f32_16x16x32_bf16 v[32:35], v[156:159], v[224:227], v[32:35]
	v_mfma_f32_16x16x32_bf16 v[24:27], v[164:167], v[224:227], v[24:27]
	v_mfma_f32_16x16x32_bf16 v[16:19], v[156:159], v[232:235], v[16:19]
	v_mfma_f32_16x16x32_bf16 v[8:11], v[164:167], v[232:235], v[8:11]
	v_mfma_f32_16x16x32_bf16 v[64:67], v[160:163], v[212:215], v[64:67]
	v_mfma_f32_16x16x32_bf16 v[56:59], v[168:171], v[212:215], v[56:59]
	v_mfma_f32_16x16x32_bf16 v[48:51], v[160:163], v[220:223], v[48:51]
	v_mfma_f32_16x16x32_bf16 v[40:43], v[168:171], v[220:223], v[40:43]
	v_mfma_f32_16x16x32_bf16 v[32:35], v[160:163], v[228:231], v[32:35]
	v_mfma_f32_16x16x32_bf16 v[24:27], v[168:171], v[228:231], v[24:27]
	v_mfma_f32_16x16x32_bf16 v[16:19], v[160:163], v[236:239], v[16:19]
	v_mfma_f32_16x16x32_bf16 v[8:11], v[168:171], v[236:239], v[8:11]
	s_setprio 0
	s_setprio 1
	v_mfma_f32_16x16x32_bf16 v[60:63], v[172:175], v[208:211], v[60:63]
	v_mfma_f32_16x16x32_bf16 v[52:55], v[180:183], v[208:211], v[52:55]
	v_mfma_f32_16x16x32_bf16 v[44:47], v[172:175], v[216:219], v[44:47]
	v_mfma_f32_16x16x32_bf16 v[36:39], v[180:183], v[216:219], v[36:39]
	v_mfma_f32_16x16x32_bf16 v[28:31], v[172:175], v[224:227], v[28:31]
	v_mfma_f32_16x16x32_bf16 v[20:23], v[180:183], v[224:227], v[20:23]
	v_mfma_f32_16x16x32_bf16 v[12:15], v[172:175], v[232:235], v[12:15]
	v_mfma_f32_16x16x32_bf16 v[4:7], v[180:183], v[232:235], v[4:7]
	v_mfma_f32_16x16x32_bf16 v[60:63], v[176:179], v[212:215], v[60:63]
	v_mfma_f32_16x16x32_bf16 v[52:55], v[184:187], v[212:215], v[52:55]
	v_mfma_f32_16x16x32_bf16 v[44:47], v[176:179], v[220:223], v[44:47]
	v_mfma_f32_16x16x32_bf16 v[36:39], v[184:187], v[220:223], v[36:39]
	v_mfma_f32_16x16x32_bf16 v[28:31], v[176:179], v[228:231], v[28:31]
	v_mfma_f32_16x16x32_bf16 v[20:23], v[184:187], v[228:231], v[20:23]
	v_mfma_f32_16x16x32_bf16 v[12:15], v[176:179], v[236:239], v[12:15]
	v_mfma_f32_16x16x32_bf16 v[4:7], v[184:187], v[236:239], v[4:7]
	s_setprio 0
	s_barrier
	s_add_i32 s15, s15, 2
	s_add_u32 s44, s44, 0x100
	s_addc_u32 s45, s45, 0
	s_add_u32 s13, s13, 0x100
	s_addc_u32 s14, s14, 0
	s_cmp_gt_u32 s15, 13
	s_cbranch_scc0 .LBB0_98
	s_lshl_b32 s5, s42, 8
	s_and_b64 vcc, exec, s[2:3]
	s_cbranch_vccz .LBB0_101
	v_or_b32_e32 v148, s5, v152
	v_ashrrev_i32_e32 v149, 31, v148
	v_readlane_b32 s10, v255, 11
	v_lshlrev_b64 v[148:149], 6, v[148:149]
	v_readlane_b32 s11, v255, 12
	s_nop 1
	v_lshl_add_u64 v[148:149], s[10:11], 0, v[148:149]
	global_load_dwordx4 v[156:159], v[148:149], off
	global_load_dwordx4 v[160:163], v[148:149], off offset:32
	global_load_dwordx4 v[164:167], v[148:149], off offset:16
	global_load_dwordx4 v[168:171], v[148:149], off offset:48
	s_barrier

.LBB0_504:
	s_add_u32 s10, s16, s44
	s_addc_u32 s11, s17, s45
	s_add_u32 s10, s10, 0x100
	s_addc_u32 s11, s11, 0
	s_add_u32 s18, s13, s44
	s_addc_u32 s19, s14, s45
	s_cmpk_eq_i32 s44, 0xb00
	s_cselect_b32 s25, s5, s11
	s_cselect_b32 s24, s4, s10
	s_cselect_b32 s23, s7, s19
	s_cselect_b32 s22, s6, s18
	s_add_i32 s10, 0, 0x10000
	v_add_u32_e32 v0, s10, v208
	s_add_i32 s18, 0, 0x14000
	ds_read_b128 v[162:165], v0
	ds_read_b128 v[166:169], v0 offset:1024
	ds_read_b128 v[170:173], v0 offset:2048
	ds_read_b128 v[174:177], v0 offset:3072
	v_add_u32_e32 v0, s18, v208
	ds_read_b128 v[178:181], v0
	ds_read_b128 v[182:185], v0 offset:1024
	ds_read_b128 v[212:215], v0 offset:2048
	ds_read_b128 v[216:219], v0 offset:3072
	v_lshl_add_u64 v[0:1], v[158:159], 0, s[44:45]
	s_add_i32 m0, s47, 0xc000
	ds_read_b128 v[220:223], v211
	ds_read_b128 v[224:227], v211 offset:1024
	ds_read_b128 v[228:231], v211 offset:2048
	ds_read_b128 v[232:235], v211 offset:3072
	ds_read_b128 v[236:239], v211 offset:4096
	ds_read_b128 v[240:243], v211 offset:5120
	ds_read_b128 v[244:247], v211 offset:6144
	ds_read_b128 v[248:251], v211 offset:7168
	global_load_lds_dwordx4 v[0:1], off
	v_lshl_add_u64 v[0:1], v[160:161], 0, s[44:45]
	s_add_i32 m0, s47, 0xe000
	s_nop 0
	global_load_lds_dwordx4 v[0:1], off
	s_waitcnt vmcnt(8)
	s_waitcnt lgkmcnt(0)
	s_barrier
	s_setprio 1
	v_mfma_f32_16x16x32_bf16 v[128:131], v[162:165], v[220:223], v[128:131]
	v_mfma_f32_16x16x32_bf16 v[124:127], v[170:173], v[220:223], v[124:127]
	v_mfma_f32_16x16x32_bf16 v[112:115], v[162:165], v[228:231], v[112:115]
	v_mfma_f32_16x16x32_bf16 v[108:111], v[170:173], v[228:231], v[108:111]
	v_mfma_f32_16x16x32_bf16 v[96:99], v[162:165], v[236:239], v[96:99]
	v_mfma_f32_16x16x32_bf16 v[92:95], v[170:173], v[236:239], v[92:95]
	v_mfma_f32_16x16x32_bf16 v[80:83], v[162:165], v[244:247], v[80:83]
	v_mfma_f32_16x16x32_bf16 v[76:79], v[170:173], v[244:247], v[76:79]
	v_mfma_f32_16x16x32_bf16 v[128:131], v[166:169], v[224:227], v[128:131]
	v_mfma_f32_16x16x32_bf16 v[124:127], v[174:177], v[224:227], v[124:127]
	v_mfma_f32_16x16x32_bf16 v[112:115], v[166:169], v[232:235], v[112:115]
	v_mfma_f32_16x16x32_bf16 v[108:111], v[174:177], v[232:235], v[108:111]
	v_mfma_f32_16x16x32_bf16 v[96:99], v[166:169], v[240:243], v[96:99]
	v_mfma_f32_16x16x32_bf16 v[92:95], v[174:177], v[240:243], v[92:95]
	v_mfma_f32_16x16x32_bf16 v[80:83], v[166:169], v[248:251], v[80:83]
	v_mfma_f32_16x16x32_bf16 v[76:79], v[174:177], v[248:251], v[76:79]
	s_setprio 0
	s_setprio 1
	v_mfma_f32_16x16x32_bf16 v[120:123], v[178:181], v[220:223], v[120:123]
	v_mfma_f32_16x16x32_bf16 v[116:119], v[212:215], v[220:223], v[116:119]
	v_mfma_f32_16x16x32_bf16 v[104:107], v[178:181], v[228:231], v[104:107]
	v_mfma_f32_16x16x32_bf16 v[100:103], v[212:215], v[228:231], v[100:103]
	v_mfma_f32_16x16x32_bf16 v[88:91], v[178:181], v[236:239], v[88:91]
	v_mfma_f32_16x16x32_bf16 v[84:87], v[212:215], v[236:239], v[84:87]
	v_mfma_f32_16x16x32_bf16 v[72:75], v[178:181], v[244:247], v[72:75]
	v_mfma_f32_16x16x32_bf16 v[68:71], v[212:215], v[244:247], v[68:71]
	v_mfma_f32_16x16x32_bf16 v[120:123], v[182:185], v[224:227], v[120:123]
	v_mfma_f32_16x16x32_bf16 v[116:119], v[216:219], v[224:227], v[116:119]
	v_mfma_f32_16x16x32_bf16 v[104:107], v[182:185], v[232:235], v[104:107]
	v_mfma_f32_16x16x32_bf16 v[100:103], v[216:219], v[232:235], v[100:103]
	v_mfma_f32_16x16x32_bf16 v[88:91], v[182:185], v[240:243], v[88:91]
	v_mfma_f32_16x16x32_bf16 v[84:87], v[216:219], v[240:243], v[84:87]
	v_mfma_f32_16x16x32_bf16 v[72:75], v[182:185], v[248:251], v[72:75]
	v_mfma_f32_16x16x32_bf16 v[68:71], v[216:219], v[248:251], v[68:71]
	s_setprio 0
	s_barrier
	s_add_i32 s10, s10, s46
	s_mov_b32 m0, s10
	ds_read_b128 v[220:223], v211 offset:16384
	ds_read_b128 v[224:227], v211 offset:17408
	ds_read_b128 v[228:231], v211 offset:18432
	ds_read_b128 v[232:235], v211 offset:19456
	ds_read_b128 v[236:239], v211 offset:20480
	ds_read_b128 v[240:243], v211 offset:21504
	ds_read_b128 v[244:247], v211 offset:22528
	ds_read_b128 v[248:251], v211 offset:23552
	global_load_lds_dwordx4 v140, s[22:23]
	s_add_i32 m0, s10, 0x2000
	s_add_u32 s10, s22, 0x60000
	s_addc_u32 s11, s23, 0
	s_add_i32 s18, s18, s46
	global_load_lds_dwordx4 v142, s[22:23]
	s_mov_b32 m0, s18
	s_nop 0
	global_load_lds_dwordx4 v140, s[10:11]
	s_add_i32 m0, s18, 0x2000
	s_nop 0
	global_load_lds_dwordx4 v142, s[10:11]
	s_mov_b32 m0, s47
	s_nop 0
	global_load_lds_dwordx4 v140, s[24:25]
	s_mov_b32 m0, s48
	s_nop 0
	global_load_lds_dwordx4 v142, s[24:25]
	s_waitcnt vmcnt(8)
	s_waitcnt lgkmcnt(0)
	s_barrier
	s_setprio 1
	v_mfma_f32_16x16x32_bf16 v[64:67], v[162:165], v[220:223], v[64:67]
	v_mfma_f32_16x16x32_bf16 v[60:63], v[170:173], v[220:223], v[60:63]
	v_mfma_f32_16x16x32_bf16 v[48:51], v[162:165], v[228:231], v[48:51]
	v_mfma_f32_16x16x32_bf16 v[44:47], v[170:173], v[228:231], v[44:47]
	v_mfma_f32_16x16x32_bf16 v[32:35], v[162:165], v[236:239], v[32:35]
	v_mfma_f32_16x16x32_bf16 v[28:31], v[170:173], v[236:239], v[28:31]
	v_mfma_f32_16x16x32_bf16 v[16:19], v[162:165], v[244:247], v[16:19]
	v_mfma_f32_16x16x32_bf16 v[12:15], v[170:173], v[244:247], v[12:15]
	v_mfma_f32_16x16x32_bf16 v[64:67], v[166:169], v[224:227], v[64:67]
	v_mfma_f32_16x16x32_bf16 v[60:63], v[174:177], v[224:227], v[60:63]
	v_mfma_f32_16x16x32_bf16 v[48:51], v[166:169], v[232:235], v[48:51]
	v_mfma_f32_16x16x32_bf16 v[44:47], v[174:177], v[232:235], v[44:47]
	v_mfma_f32_16x16x32_bf16 v[32:35], v[166:169], v[240:243], v[32:35]
	v_mfma_f32_16x16x32_bf16 v[28:31], v[174:177], v[240:243], v[28:31]
	v_mfma_f32_16x16x32_bf16 v[16:19], v[166:169], v[248:251], v[16:19]
	v_mfma_f32_16x16x32_bf16 v[12:15], v[174:177], v[248:251], v[12:15]
	s_setprio 0
	s_setprio 1
	v_mfma_f32_16x16x32_bf16 v[56:59], v[178:181], v[220:223], v[56:59]
	v_mfma_f32_16x16x32_bf16 v[52:55], v[212:215], v[220:223], v[52:55]
	v_mfma_f32_16x16x32_bf16 v[40:43], v[178:181], v[228:231], v[40:43]
	v_mfma_f32_16x16x32_bf16 v[36:39], v[212:215], v[228:231], v[36:39]
	v_mfma_f32_16x16x32_bf16 v[24:27], v[178:181], v[236:239], v[24:27]
	v_mfma_f32_16x16x32_bf16 v[20:23], v[212:215], v[236:239], v[20:23]
	v_mfma_f32_16x16x32_bf16 v[8:11], v[178:181], v[244:247], v[8:11]
	v_mfma_f32_16x16x32_bf16 v[4:7], v[212:215], v[244:247], v[4:7]
	v_mfma_f32_16x16x32_bf16 v[56:59], v[182:185], v[224:227], v[56:59]
	v_mfma_f32_16x16x32_bf16 v[52:55], v[216:219], v[224:227], v[52:55]
	v_mfma_f32_16x16x32_bf16 v[40:43], v[182:185], v[232:235], v[40:43]
	v_mfma_f32_16x16x32_bf16 v[36:39], v[216:219], v[232:235], v[36:39]
	v_mfma_f32_16x16x32_bf16 v[24:27], v[182:185], v[240:243], v[24:27]
	v_mfma_f32_16x16x32_bf16 v[20:23], v[216:219], v[240:243], v[20:23]
	v_mfma_f32_16x16x32_bf16 v[8:11], v[182:185], v[248:251], v[8:11]
	v_mfma_f32_16x16x32_bf16 v[4:7], v[216:219], v[248:251], v[4:7]
	s_setprio 0
	s_barrier
	s_add_i32 s18, 0, 0x18000
	v_add_u32_e32 v2, s18, v208
	s_add_i32 s19, 0, 0x1c000
	ds_read_b128 v[162:165], v2
	ds_read_b128 v[166:169], v2 offset:1024
	ds_read_b128 v[170:173], v2 offset:2048
	ds_read_b128 v[174:177], v2 offset:3072
	v_add_u32_e32 v2, s19, v208
	ds_read_b128 v[178:181], v2
	ds_read_b128 v[182:185], v2 offset:1024
	ds_read_b128 v[212:215], v2 offset:2048
	ds_read_b128 v[216:219], v2 offset:3072
	s_add_u32 s10, s24, 0x60000
	s_addc_u32 s11, s25, 0
	s_mov_b32 m0, s49
	ds_read_b128 v[220:223], v211 offset:32768
	ds_read_b128 v[224:227], v211 offset:33792
	ds_read_b128 v[228:231], v211 offset:34816
	ds_read_b128 v[232:235], v211 offset:35840
	ds_read_b128 v[236:239], v211 offset:36864
	ds_read_b128 v[240:243], v211 offset:37888
	ds_read_b128 v[244:247], v211 offset:38912
	ds_read_b128 v[248:251], v211 offset:39936
	global_load_lds_dwordx4 v140, s[10:11]
	s_mov_b32 m0, s50
	s_nop 0
	global_load_lds_dwordx4 v142, s[10:11]
	s_waitcnt vmcnt(8)
	s_waitcnt lgkmcnt(0)
	s_barrier
	s_setprio 1
	v_mfma_f32_16x16x32_bf16 v[128:131], v[162:165], v[220:223], v[128:131]
	v_mfma_f32_16x16x32_bf16 v[124:127], v[170:173], v[220:223], v[124:127]
	v_mfma_f32_16x16x32_bf16 v[112:115], v[162:165], v[228:231], v[112:115]
	v_mfma_f32_16x16x32_bf16 v[108:111], v[170:173], v[228:231], v[108:111]
	v_mfma_f32_16x16x32_bf16 v[96:99], v[162:165], v[236:239], v[96:99]
	v_mfma_f32_16x16x32_bf16 v[92:95], v[170:173], v[236:239], v[92:95]
	v_mfma_f32_16x16x32_bf16 v[80:83], v[162:165], v[244:247], v[80:83]
	v_mfma_f32_16x16x32_bf16 v[76:79], v[170:173], v[244:247], v[76:79]
	v_mfma_f32_16x16x32_bf16 v[128:131], v[166:169], v[224:227], v[128:131]
	v_mfma_f32_16x16x32_bf16 v[124:127], v[174:177], v[224:227], v[124:127]
	v_mfma_f32_16x16x32_bf16 v[112:115], v[166:169], v[232:235], v[112:115]
	v_mfma_f32_16x16x32_bf16 v[108:111], v[174:177], v[232:235], v[108:111]
	v_mfma_f32_16x16x32_bf16 v[96:99], v[166:169], v[240:243], v[96:99]
	v_mfma_f32_16x16x32_bf16 v[92:95], v[174:177], v[240:243], v[92:95]
	v_mfma_f32_16x16x32_bf16 v[80:83], v[166:169], v[248:251], v[80:83]
	v_mfma_f32_16x16x32_bf16 v[76:79], v[174:177], v[248:251], v[76:79]
	s_setprio 0
	s_setprio 1
	v_mfma_f32_16x16x32_bf16 v[120:123], v[178:181], v[220:223], v[120:123]
	v_mfma_f32_16x16x32_bf16 v[116:119], v[212:215], v[220:223], v[116:119]
	v_mfma_f32_16x16x32_bf16 v[104:107], v[178:181], v[228:231], v[104:107]
	v_mfma_f32_16x16x32_bf16 v[100:103], v[212:215], v[228:231], v[100:103]
	v_mfma_f32_16x16x32_bf16 v[88:91], v[178:181], v[236:239], v[88:91]
	v_mfma_f32_16x16x32_bf16 v[84:87], v[212:215], v[236:239], v[84:87]
	v_mfma_f32_16x16x32_bf16 v[72:75], v[178:181], v[244:247], v[72:75]
	v_mfma_f32_16x16x32_bf16 v[68:71], v[212:215], v[244:247], v[68:71]
	v_mfma_f32_16x16x32_bf16 v[120:123], v[182:185], v[224:227], v[120:123]
	v_mfma_f32_16x16x32_bf16 v[116:119], v[216:219], v[224:227], v[116:119]
	v_mfma_f32_16x16x32_bf16 v[104:107], v[182:185], v[232:235], v[104:107]
	v_mfma_f32_16x16x32_bf16 v[100:103], v[216:219], v[232:235], v[100:103]
	v_mfma_f32_16x16x32_bf16 v[88:91], v[182:185], v[240:243], v[88:91]
	v_mfma_f32_16x16x32_bf16 v[84:87], v[216:219], v[240:243], v[84:87]
	v_mfma_f32_16x16x32_bf16 v[72:75], v[182:185], v[248:251], v[72:75]
	v_mfma_f32_16x16x32_bf16 v[68:71], v[216:219], v[248:251], v[68:71]
	s_setprio 0
	s_barrier
	s_add_i32 s10, s18, s46
	s_add_u32 s100, s22, 0x80
	s_addc_u32 s101, s23, 0
	s_mov_b32 m0, s10
	ds_read_b128 v[220:223], v211 offset:49152
	ds_read_b128 v[224:227], v211 offset:50176
	ds_read_b128 v[228:231], v211 offset:51200
	ds_read_b128 v[232:235], v211 offset:52224
	ds_read_b128 v[236:239], v211 offset:53248
	ds_read_b128 v[240:243], v211 offset:54272
	ds_read_b128 v[244:247], v211 offset:55296
	ds_read_b128 v[248:251], v211 offset:56320
	global_load_lds_dwordx4 v140, s[100:101]
	s_add_i32 m0, s10, 0x2000
	s_add_u32 s10, s22, 0x60080
	s_addc_u32 s11, s23, 0
	s_add_i32 s18, s19, s46
	global_load_lds_dwordx4 v142, s[100:101]
	s_mov_b32 m0, s18
	s_nop 0
	global_load_lds_dwordx4 v140, s[10:11]
	s_add_i32 m0, s18, 0x2000
	s_nop 0
	global_load_lds_dwordx4 v142, s[10:11]
	s_add_u32 s100, s24, 0x80
	s_addc_u32 s101, s25, 0
	s_mov_b32 m0, s52
	s_nop 0
	global_load_lds_dwordx4 v140, s[100:101]
	s_mov_b32 m0, s53
	s_nop 0
	global_load_lds_dwordx4 v142, s[100:101]
	s_waitcnt vmcnt(8)
	s_waitcnt lgkmcnt(0)
	s_barrier
	s_setprio 1
	v_mfma_f32_16x16x32_bf16 v[64:67], v[162:165], v[220:223], v[64:67]
	v_mfma_f32_16x16x32_bf16 v[60:63], v[170:173], v[220:223], v[60:63]
	v_mfma_f32_16x16x32_bf16 v[48:51], v[162:165], v[228:231], v[48:51]
	v_mfma_f32_16x16x32_bf16 v[44:47], v[170:173], v[228:231], v[44:47]
	v_mfma_f32_16x16x32_bf16 v[32:35], v[162:165], v[236:239], v[32:35]
	v_mfma_f32_16x16x32_bf16 v[28:31], v[170:173], v[236:239], v[28:31]
	v_mfma_f32_16x16x32_bf16 v[16:19], v[162:165], v[244:247], v[16:19]
	v_mfma_f32_16x16x32_bf16 v[12:15], v[170:173], v[244:247], v[12:15]
	v_mfma_f32_16x16x32_bf16 v[64:67], v[166:169], v[224:227], v[64:67]
	v_mfma_f32_16x16x32_bf16 v[60:63], v[174:177], v[224:227], v[60:63]
	v_mfma_f32_16x16x32_bf16 v[48:51], v[166:169], v[232:235], v[48:51]
	v_mfma_f32_16x16x32_bf16 v[44:47], v[174:177], v[232:235], v[44:47]
	v_mfma_f32_16x16x32_bf16 v[32:35], v[166:169], v[240:243], v[32:35]
	v_mfma_f32_16x16x32_bf16 v[28:31], v[174:177], v[240:243], v[28:31]
	v_mfma_f32_16x16x32_bf16 v[16:19], v[166:169], v[248:251], v[16:19]
	v_mfma_f32_16x16x32_bf16 v[12:15], v[174:177], v[248:251], v[12:15]
	s_setprio 0
	s_setprio 1
	v_mfma_f32_16x16x32_bf16 v[56:59], v[178:181], v[220:223], v[56:59]
	v_mfma_f32_16x16x32_bf16 v[52:55], v[212:215], v[220:223], v[52:55]
	v_mfma_f32_16x16x32_bf16 v[40:43], v[178:181], v[228:231], v[40:43]
	v_mfma_f32_16x16x32_bf16 v[36:39], v[212:215], v[228:231], v[36:39]
	v_mfma_f32_16x16x32_bf16 v[24:27], v[178:181], v[236:239], v[24:27]
	v_mfma_f32_16x16x32_bf16 v[20:23], v[212:215], v[236:239], v[20:23]
	v_mfma_f32_16x16x32_bf16 v[8:11], v[178:181], v[244:247], v[8:11]
	v_mfma_f32_16x16x32_bf16 v[4:7], v[212:215], v[244:247], v[4:7]
	v_mfma_f32_16x16x32_bf16 v[56:59], v[182:185], v[224:227], v[56:59]
	v_mfma_f32_16x16x32_bf16 v[52:55], v[216:219], v[224:227], v[52:55]
	v_mfma_f32_16x16x32_bf16 v[40:43], v[182:185], v[232:235], v[40:43]
	v_mfma_f32_16x16x32_bf16 v[36:39], v[216:219], v[232:235], v[36:39]
	v_mfma_f32_16x16x32_bf16 v[24:27], v[182:185], v[240:243], v[24:27]
	v_mfma_f32_16x16x32_bf16 v[20:23], v[216:219], v[240:243], v[20:23]
	v_mfma_f32_16x16x32_bf16 v[8:11], v[182:185], v[248:251], v[8:11]
	v_mfma_f32_16x16x32_bf16 v[4:7], v[216:219], v[248:251], v[4:7]
	s_setprio 0
	s_barrier
	s_add_i32 s10, s15, 2
	s_add_u32 s44, s44, 0x100
	s_addc_u32 s45, s45, 0
	s_cmp_gt_u32 s15, 21
	s_cbranch_scc1 .LBB0_513
	s_mov_b32 s15, s10
	s_cmp_lt_i32 s15, 16
	s_cbranch_scc1 .LBB0_490

.LBB0_811:
	s_add_u32 s42, s44, 0x100
	s_addc_u32 s43, s45, 0
	s_add_i32 s18, 0, 0x10000
	s_cmp_eq_u32 s15, 40
	s_cselect_b32 s25, s11, s43
	s_cselect_b32 s24, s10, s42
	s_cselect_b32 s23, s17, s14
	s_cselect_b32 s22, s16, s13
	s_add_i32 s62, 0, 0x14000
	ds_read_b128 v[144:147], v213
	ds_read_b128 v[148:151], v213 offset:1024
	ds_read_b128 v[152:155], v213 offset:2048
	ds_read_b128 v[156:159], v213 offset:3072
	ds_read_b128 v[160:163], v213 offset:16384
	ds_read_b128 v[164:167], v213 offset:17408
	ds_read_b128 v[168:171], v213 offset:18432
	ds_read_b128 v[172:175], v213 offset:19456
	s_add_i32 m0, s47, 0xc000
	ds_read_b128 v[176:179], v212
	ds_read_b128 v[180:183], v212 offset:1024
	ds_read_b128 v[184:187], v212 offset:2048
	ds_read_b128 v[214:217], v212 offset:3072
	ds_read_b128 v[218:221], v212 offset:4096
	ds_read_b128 v[222:225], v212 offset:5120
	ds_read_b128 v[226:229], v212 offset:6144
	ds_read_b128 v[230:233], v212 offset:7168
	global_load_lds_dwordx4 v140, s[44:45]
	s_add_i32 m0, s47, 0xe000
	s_nop 0
	global_load_lds_dwordx4 v142, s[44:45]
	s_waitcnt vmcnt(8)
	s_waitcnt lgkmcnt(0)
	s_barrier
	s_setprio 1
	v_mfma_f32_16x16x32_bf16 v[128:131], v[144:147], v[176:179], v[128:131]
	v_mfma_f32_16x16x32_bf16 v[124:127], v[152:155], v[176:179], v[124:127]
	v_mfma_f32_16x16x32_bf16 v[112:115], v[144:147], v[184:187], v[112:115]
	v_mfma_f32_16x16x32_bf16 v[108:111], v[152:155], v[184:187], v[108:111]
	v_mfma_f32_16x16x32_bf16 v[96:99], v[144:147], v[218:221], v[96:99]
	v_mfma_f32_16x16x32_bf16 v[92:95], v[152:155], v[218:221], v[92:95]
	v_mfma_f32_16x16x32_bf16 v[80:83], v[144:147], v[226:229], v[80:83]
	v_mfma_f32_16x16x32_bf16 v[76:79], v[152:155], v[226:229], v[76:79]
	v_mfma_f32_16x16x32_bf16 v[128:131], v[148:151], v[180:183], v[128:131]
	v_mfma_f32_16x16x32_bf16 v[124:127], v[156:159], v[180:183], v[124:127]
	v_mfma_f32_16x16x32_bf16 v[112:115], v[148:151], v[214:217], v[112:115]
	v_mfma_f32_16x16x32_bf16 v[108:111], v[156:159], v[214:217], v[108:111]
	v_mfma_f32_16x16x32_bf16 v[96:99], v[148:151], v[222:225], v[96:99]
	v_mfma_f32_16x16x32_bf16 v[92:95], v[156:159], v[222:225], v[92:95]
	v_mfma_f32_16x16x32_bf16 v[80:83], v[148:151], v[230:233], v[80:83]
	v_mfma_f32_16x16x32_bf16 v[76:79], v[156:159], v[230:233], v[76:79]
	s_setprio 0
	s_setprio 1
	v_mfma_f32_16x16x32_bf16 v[120:123], v[160:163], v[176:179], v[120:123]
	v_mfma_f32_16x16x32_bf16 v[116:119], v[168:171], v[176:179], v[116:119]
	v_mfma_f32_16x16x32_bf16 v[104:107], v[160:163], v[184:187], v[104:107]
	v_mfma_f32_16x16x32_bf16 v[100:103], v[168:171], v[184:187], v[100:103]
	v_mfma_f32_16x16x32_bf16 v[88:91], v[160:163], v[218:221], v[88:91]
	v_mfma_f32_16x16x32_bf16 v[84:87], v[168:171], v[218:221], v[84:87]
	v_mfma_f32_16x16x32_bf16 v[72:75], v[160:163], v[226:229], v[72:75]
	v_mfma_f32_16x16x32_bf16 v[68:71], v[168:171], v[226:229], v[68:71]
	v_mfma_f32_16x16x32_bf16 v[120:123], v[164:167], v[180:183], v[120:123]
	v_mfma_f32_16x16x32_bf16 v[116:119], v[172:175], v[180:183], v[116:119]
	v_mfma_f32_16x16x32_bf16 v[104:107], v[164:167], v[214:217], v[104:107]
	v_mfma_f32_16x16x32_bf16 v[100:103], v[172:175], v[214:217], v[100:103]
	v_mfma_f32_16x16x32_bf16 v[88:91], v[164:167], v[222:225], v[88:91]
	v_mfma_f32_16x16x32_bf16 v[84:87], v[172:175], v[222:225], v[84:87]
	v_mfma_f32_16x16x32_bf16 v[72:75], v[164:167], v[230:233], v[72:75]
	v_mfma_f32_16x16x32_bf16 v[68:71], v[172:175], v[230:233], v[68:71]
	s_setprio 0
	s_barrier
	s_add_i32 s18, s18, s46
	s_mov_b32 m0, s18
	ds_read_b128 v[176:179], v212 offset:16384
	ds_read_b128 v[180:183], v212 offset:17408
	ds_read_b128 v[184:187], v212 offset:18432
	ds_read_b128 v[214:217], v212 offset:19456
	ds_read_b128 v[218:221], v212 offset:20480
	ds_read_b128 v[222:225], v212 offset:21504
	ds_read_b128 v[226:229], v212 offset:22528
	ds_read_b128 v[230:233], v212 offset:23552
	global_load_lds_dwordx4 v2, s[22:23]
	s_add_i32 m0, s18, 0x2000
	s_add_u32 s18, s22, 0xb0000
	s_addc_u32 s19, s23, 0
	s_add_i32 s44, s62, s46
	global_load_lds_dwordx4 v0, s[22:23]
	s_mov_b32 m0, s44
	s_nop 0
	global_load_lds_dwordx4 v2, s[18:19]
	s_add_i32 m0, s44, 0x2000
	s_nop 0
	global_load_lds_dwordx4 v0, s[18:19]
	s_mov_b32 m0, s47
	s_nop 0
	global_load_lds_dwordx4 v2, s[24:25]
	s_mov_b32 m0, s48
	s_nop 0
	global_load_lds_dwordx4 v0, s[24:25]
	s_waitcnt vmcnt(8)
	s_waitcnt lgkmcnt(0)
	s_barrier
	s_setprio 1
	v_mfma_f32_16x16x32_bf16 v[64:67], v[144:147], v[176:179], v[64:67]
	v_mfma_f32_16x16x32_bf16 v[60:63], v[152:155], v[176:179], v[60:63]
	v_mfma_f32_16x16x32_bf16 v[48:51], v[144:147], v[184:187], v[48:51]
	v_mfma_f32_16x16x32_bf16 v[44:47], v[152:155], v[184:187], v[44:47]
	v_mfma_f32_16x16x32_bf16 v[32:35], v[144:147], v[218:221], v[32:35]
	v_mfma_f32_16x16x32_bf16 v[28:31], v[152:155], v[218:221], v[28:31]
	v_mfma_f32_16x16x32_bf16 v[16:19], v[144:147], v[226:229], v[16:19]
	v_mfma_f32_16x16x32_bf16 v[12:15], v[152:155], v[226:229], v[12:15]
	v_mfma_f32_16x16x32_bf16 v[64:67], v[148:151], v[180:183], v[64:67]
	v_mfma_f32_16x16x32_bf16 v[60:63], v[156:159], v[180:183], v[60:63]
	v_mfma_f32_16x16x32_bf16 v[48:51], v[148:151], v[214:217], v[48:51]
	v_mfma_f32_16x16x32_bf16 v[44:47], v[156:159], v[214:217], v[44:47]
	v_mfma_f32_16x16x32_bf16 v[32:35], v[148:151], v[222:225], v[32:35]
	v_mfma_f32_16x16x32_bf16 v[28:31], v[156:159], v[222:225], v[28:31]
	v_mfma_f32_16x16x32_bf16 v[16:19], v[148:151], v[230:233], v[16:19]
	v_mfma_f32_16x16x32_bf16 v[12:15], v[156:159], v[230:233], v[12:15]
	s_setprio 0
	s_setprio 1
	v_mfma_f32_16x16x32_bf16 v[56:59], v[160:163], v[176:179], v[56:59]
	v_mfma_f32_16x16x32_bf16 v[52:55], v[168:171], v[176:179], v[52:55]
	v_mfma_f32_16x16x32_bf16 v[40:43], v[160:163], v[184:187], v[40:43]
	v_mfma_f32_16x16x32_bf16 v[36:39], v[168:171], v[184:187], v[36:39]
	v_mfma_f32_16x16x32_bf16 v[24:27], v[160:163], v[218:221], v[24:27]
	v_mfma_f32_16x16x32_bf16 v[20:23], v[168:171], v[218:221], v[20:23]
	v_mfma_f32_16x16x32_bf16 v[8:11], v[160:163], v[226:229], v[8:11]
	v_mfma_f32_16x16x32_bf16 v[4:7], v[168:171], v[226:229], v[4:7]
	v_mfma_f32_16x16x32_bf16 v[56:59], v[164:167], v[180:183], v[56:59]
	v_mfma_f32_16x16x32_bf16 v[52:55], v[172:175], v[180:183], v[52:55]
	v_mfma_f32_16x16x32_bf16 v[40:43], v[164:167], v[214:217], v[40:43]
	v_mfma_f32_16x16x32_bf16 v[36:39], v[172:175], v[214:217], v[36:39]
	v_mfma_f32_16x16x32_bf16 v[24:27], v[164:167], v[222:225], v[24:27]
	v_mfma_f32_16x16x32_bf16 v[20:23], v[172:175], v[222:225], v[20:23]
	v_mfma_f32_16x16x32_bf16 v[8:11], v[164:167], v[230:233], v[8:11]
	v_mfma_f32_16x16x32_bf16 v[4:7], v[172:175], v[230:233], v[4:7]
	s_setprio 0
	s_barrier
	s_add_i32 s44, 0, 0x18000
	s_add_i32 s45, 0, 0x1c000
	ds_read_b128 v[144:147], v213 offset:32768
	ds_read_b128 v[148:151], v213 offset:33792
	ds_read_b128 v[152:155], v213 offset:34816
	ds_read_b128 v[156:159], v213 offset:35840
	ds_read_b128 v[160:163], v213 offset:49152
	ds_read_b128 v[164:167], v213 offset:50176
	ds_read_b128 v[168:171], v213 offset:51200
	ds_read_b128 v[172:175], v213 offset:52224
	s_add_u32 s18, s24, 0xb0000
	s_addc_u32 s19, s25, 0
	s_mov_b32 m0, s49
	ds_read_b128 v[176:179], v212 offset:32768
	ds_read_b128 v[180:183], v212 offset:33792
	ds_read_b128 v[184:187], v212 offset:34816
	ds_read_b128 v[214:217], v212 offset:35840
	ds_read_b128 v[218:221], v212 offset:36864
	ds_read_b128 v[222:225], v212 offset:37888
	ds_read_b128 v[226:229], v212 offset:38912
	ds_read_b128 v[230:233], v212 offset:39936
	global_load_lds_dwordx4 v2, s[18:19]
	s_mov_b32 m0, s50
	s_nop 0
	global_load_lds_dwordx4 v0, s[18:19]
	s_waitcnt vmcnt(8)
	s_waitcnt lgkmcnt(0)
	s_barrier
	s_setprio 1
	v_mfma_f32_16x16x32_bf16 v[128:131], v[144:147], v[176:179], v[128:131]
	v_mfma_f32_16x16x32_bf16 v[124:127], v[152:155], v[176:179], v[124:127]
	v_mfma_f32_16x16x32_bf16 v[112:115], v[144:147], v[184:187], v[112:115]
	v_mfma_f32_16x16x32_bf16 v[108:111], v[152:155], v[184:187], v[108:111]
	v_mfma_f32_16x16x32_bf16 v[96:99], v[144:147], v[218:221], v[96:99]
	v_mfma_f32_16x16x32_bf16 v[92:95], v[152:155], v[218:221], v[92:95]
	v_mfma_f32_16x16x32_bf16 v[80:83], v[144:147], v[226:229], v[80:83]
	v_mfma_f32_16x16x32_bf16 v[76:79], v[152:155], v[226:229], v[76:79]
	v_mfma_f32_16x16x32_bf16 v[128:131], v[148:151], v[180:183], v[128:131]
	v_mfma_f32_16x16x32_bf16 v[124:127], v[156:159], v[180:183], v[124:127]
	v_mfma_f32_16x16x32_bf16 v[112:115], v[148:151], v[214:217], v[112:115]
	v_mfma_f32_16x16x32_bf16 v[108:111], v[156:159], v[214:217], v[108:111]
	v_mfma_f32_16x16x32_bf16 v[96:99], v[148:151], v[222:225], v[96:99]
	v_mfma_f32_16x16x32_bf16 v[92:95], v[156:159], v[222:225], v[92:95]
	v_mfma_f32_16x16x32_bf16 v[80:83], v[148:151], v[230:233], v[80:83]
	v_mfma_f32_16x16x32_bf16 v[76:79], v[156:159], v[230:233], v[76:79]
	s_setprio 0
	s_setprio 1
	v_mfma_f32_16x16x32_bf16 v[120:123], v[160:163], v[176:179], v[120:123]
	v_mfma_f32_16x16x32_bf16 v[116:119], v[168:171], v[176:179], v[116:119]
	v_mfma_f32_16x16x32_bf16 v[104:107], v[160:163], v[184:187], v[104:107]
	v_mfma_f32_16x16x32_bf16 v[100:103], v[168:171], v[184:187], v[100:103]
	v_mfma_f32_16x16x32_bf16 v[88:91], v[160:163], v[218:221], v[88:91]
	v_mfma_f32_16x16x32_bf16 v[84:87], v[168:171], v[218:221], v[84:87]
	v_mfma_f32_16x16x32_bf16 v[72:75], v[160:163], v[226:229], v[72:75]
	v_mfma_f32_16x16x32_bf16 v[68:71], v[168:171], v[226:229], v[68:71]
	v_mfma_f32_16x16x32_bf16 v[120:123], v[164:167], v[180:183], v[120:123]
	v_mfma_f32_16x16x32_bf16 v[116:119], v[172:175], v[180:183], v[116:119]
	v_mfma_f32_16x16x32_bf16 v[104:107], v[164:167], v[214:217], v[104:107]
	v_mfma_f32_16x16x32_bf16 v[100:103], v[172:175], v[214:217], v[100:103]
	v_mfma_f32_16x16x32_bf16 v[88:91], v[164:167], v[222:225], v[88:91]
	v_mfma_f32_16x16x32_bf16 v[84:87], v[172:175], v[222:225], v[84:87]
	v_mfma_f32_16x16x32_bf16 v[72:75], v[164:167], v[230:233], v[72:75]
	v_mfma_f32_16x16x32_bf16 v[68:71], v[172:175], v[230:233], v[68:71]
	s_setprio 0
	s_barrier
	s_add_i32 s18, s44, s46
	s_add_u32 s100, s22, 0x80
	s_addc_u32 s101, s23, 0
	s_mov_b32 m0, s18
	ds_read_b128 v[176:179], v212 offset:49152
	ds_read_b128 v[180:183], v212 offset:50176
	ds_read_b128 v[184:187], v212 offset:51200
	ds_read_b128 v[214:217], v212 offset:52224
	ds_read_b128 v[218:221], v212 offset:53248
	ds_read_b128 v[222:225], v212 offset:54272
	ds_read_b128 v[226:229], v212 offset:55296
	ds_read_b128 v[230:233], v212 offset:56320
	global_load_lds_dwordx4 v2, s[100:101]
	s_add_i32 m0, s18, 0x2000
	s_add_u32 s18, s22, 0xb0080
	s_addc_u32 s19, s23, 0
	s_add_i32 s22, s45, s46
	global_load_lds_dwordx4 v0, s[100:101]
	s_mov_b32 m0, s22
	s_nop 0
	global_load_lds_dwordx4 v2, s[18:19]
	s_add_i32 m0, s22, 0x2000
	s_nop 0
	global_load_lds_dwordx4 v0, s[18:19]
	s_add_u32 s100, s24, 0x80
	s_addc_u32 s101, s25, 0
	s_mov_b32 m0, s52
	s_nop 0
	global_load_lds_dwordx4 v2, s[100:101]
	s_mov_b32 m0, s53
	s_nop 0
	global_load_lds_dwordx4 v0, s[100:101]
	s_waitcnt vmcnt(8)
	s_waitcnt lgkmcnt(0)
	s_barrier
	s_setprio 1
	v_mfma_f32_16x16x32_bf16 v[64:67], v[144:147], v[176:179], v[64:67]
	v_mfma_f32_16x16x32_bf16 v[60:63], v[152:155], v[176:179], v[60:63]
	v_mfma_f32_16x16x32_bf16 v[48:51], v[144:147], v[184:187], v[48:51]
	v_mfma_f32_16x16x32_bf16 v[44:47], v[152:155], v[184:187], v[44:47]
	v_mfma_f32_16x16x32_bf16 v[32:35], v[144:147], v[218:221], v[32:35]
	v_mfma_f32_16x16x32_bf16 v[28:31], v[152:155], v[218:221], v[28:31]
	v_mfma_f32_16x16x32_bf16 v[16:19], v[144:147], v[226:229], v[16:19]
	v_mfma_f32_16x16x32_bf16 v[12:15], v[152:155], v[226:229], v[12:15]
	v_mfma_f32_16x16x32_bf16 v[64:67], v[148:151], v[180:183], v[64:67]
	v_mfma_f32_16x16x32_bf16 v[60:63], v[156:159], v[180:183], v[60:63]
	v_mfma_f32_16x16x32_bf16 v[48:51], v[148:151], v[214:217], v[48:51]
	v_mfma_f32_16x16x32_bf16 v[44:47], v[156:159], v[214:217], v[44:47]
	v_mfma_f32_16x16x32_bf16 v[32:35], v[148:151], v[222:225], v[32:35]
	v_mfma_f32_16x16x32_bf16 v[28:31], v[156:159], v[222:225], v[28:31]
	v_mfma_f32_16x16x32_bf16 v[16:19], v[148:151], v[230:233], v[16:19]
	v_mfma_f32_16x16x32_bf16 v[12:15], v[156:159], v[230:233], v[12:15]
	s_setprio 0
	s_setprio 1
	v_mfma_f32_16x16x32_bf16 v[56:59], v[160:163], v[176:179], v[56:59]
	v_mfma_f32_16x16x32_bf16 v[52:55], v[168:171], v[176:179], v[52:55]
	v_mfma_f32_16x16x32_bf16 v[40:43], v[160:163], v[184:187], v[40:43]
	v_mfma_f32_16x16x32_bf16 v[36:39], v[168:171], v[184:187], v[36:39]
	v_mfma_f32_16x16x32_bf16 v[24:27], v[160:163], v[218:221], v[24:27]
	v_mfma_f32_16x16x32_bf16 v[20:23], v[168:171], v[218:221], v[20:23]
	v_mfma_f32_16x16x32_bf16 v[8:11], v[160:163], v[226:229], v[8:11]
	v_mfma_f32_16x16x32_bf16 v[4:7], v[168:171], v[226:229], v[4:7]
	v_mfma_f32_16x16x32_bf16 v[56:59], v[164:167], v[180:183], v[56:59]
	v_mfma_f32_16x16x32_bf16 v[52:55], v[172:175], v[180:183], v[52:55]
	v_mfma_f32_16x16x32_bf16 v[40:43], v[164:167], v[214:217], v[40:43]
	v_mfma_f32_16x16x32_bf16 v[36:39], v[172:175], v[214:217], v[36:39]
	v_mfma_f32_16x16x32_bf16 v[24:27], v[164:167], v[222:225], v[24:27]
	v_mfma_f32_16x16x32_bf16 v[20:23], v[172:175], v[222:225], v[20:23]
	v_mfma_f32_16x16x32_bf16 v[8:11], v[164:167], v[230:233], v[8:11]
	v_mfma_f32_16x16x32_bf16 v[4:7], v[172:175], v[230:233], v[4:7]
	s_setprio 0
	s_barrier
	s_add_i32 s15, s15, 2
	s_add_u32 s13, s13, 0x100
	s_addc_u32 s14, s14, 0
	s_cmp_gt_u32 s15, 41
	s_mov_b64 s[44:45], s[42:43]
	s_cbranch_scc0 .LBB0_811
	s_and_b64 vcc, exec, s[4:5]
	s_cbranch_vccz .LBB0_814
	s_barrier

.LBB0_928:
	s_add_u32 s18, s40, 0xfffc0080
	s_addc_u32 s19, s41, -1
	s_add_i32 s52, 0, 0x10000
	s_cmp_eq_u32 s51, 12
	s_cselect_b32 s25, s7, s19
	s_cselect_b32 s24, s13, s18
	s_cselect_b32 s23, s5, s43
	s_cselect_b32 s22, s17, s42
	s_add_i32 s53, 0, 0x14000
	ds_read_b128 v[148:151], v246
	ds_read_b128 v[158:161], v246 offset:1024
	ds_read_b128 v[162:165], v246 offset:2048
	ds_read_b128 v[166:169], v246 offset:3072
	ds_read_b128 v[170:173], v246 offset:16384
	ds_read_b128 v[174:177], v246 offset:17408
	ds_read_b128 v[178:181], v246 offset:18432
	ds_read_b128 v[182:185], v246 offset:19456
	s_add_i32 m0, s29, 0xc000
	ds_read_b128 v[186:189], v157
	ds_read_b128 v[208:211], v157 offset:1024
	ds_read_b128 v[212:215], v157 offset:2048
	ds_read_b128 v[216:219], v157 offset:3072
	ds_read_b128 v[220:223], v157 offset:4096
	ds_read_b128 v[224:227], v157 offset:5120
	ds_read_b128 v[228:231], v157 offset:6144
	ds_read_b128 v[232:235], v157 offset:7168
	global_load_lds_dwordx4 v144, s[40:41]
	s_add_i32 m0, s29, 0xe000
	s_nop 0
	global_load_lds_dwordx4 v146, s[40:41]
	s_waitcnt vmcnt(8)
	s_waitcnt lgkmcnt(0)
	s_barrier
	s_setprio 1
	v_mfma_f32_16x16x32_bf16 v[128:131], v[148:151], v[186:189], v[128:131]
	v_mfma_f32_16x16x32_bf16 v[124:127], v[162:165], v[186:189], v[124:127]
	v_mfma_f32_16x16x32_bf16 v[116:119], v[148:151], v[212:215], v[116:119]
	v_mfma_f32_16x16x32_bf16 v[108:111], v[162:165], v[212:215], v[108:111]
	v_mfma_f32_16x16x32_bf16 v[100:103], v[148:151], v[220:223], v[100:103]
	v_mfma_f32_16x16x32_bf16 v[92:95], v[162:165], v[220:223], v[92:95]
	v_mfma_f32_16x16x32_bf16 v[84:87], v[148:151], v[228:231], v[84:87]
	v_mfma_f32_16x16x32_bf16 v[76:79], v[162:165], v[228:231], v[76:79]
	v_mfma_f32_16x16x32_bf16 v[128:131], v[158:161], v[208:211], v[128:131]
	v_mfma_f32_16x16x32_bf16 v[124:127], v[166:169], v[208:211], v[124:127]
	v_mfma_f32_16x16x32_bf16 v[116:119], v[158:161], v[216:219], v[116:119]
	v_mfma_f32_16x16x32_bf16 v[108:111], v[166:169], v[216:219], v[108:111]
	v_mfma_f32_16x16x32_bf16 v[100:103], v[158:161], v[224:227], v[100:103]
	v_mfma_f32_16x16x32_bf16 v[92:95], v[166:169], v[224:227], v[92:95]
	v_mfma_f32_16x16x32_bf16 v[84:87], v[158:161], v[232:235], v[84:87]
	v_mfma_f32_16x16x32_bf16 v[76:79], v[166:169], v[232:235], v[76:79]
	s_setprio 0
	s_setprio 1
	v_mfma_f32_16x16x32_bf16 v[120:123], v[170:173], v[186:189], v[120:123]
	v_mfma_f32_16x16x32_bf16 v[112:115], v[178:181], v[186:189], v[112:115]
	v_mfma_f32_16x16x32_bf16 v[104:107], v[170:173], v[212:215], v[104:107]
	v_mfma_f32_16x16x32_bf16 v[96:99], v[178:181], v[212:215], v[96:99]
	v_mfma_f32_16x16x32_bf16 v[88:91], v[170:173], v[220:223], v[88:91]
	v_mfma_f32_16x16x32_bf16 v[80:83], v[178:181], v[220:223], v[80:83]
	v_mfma_f32_16x16x32_bf16 v[72:75], v[170:173], v[228:231], v[72:75]
	v_mfma_f32_16x16x32_bf16 v[68:71], v[178:181], v[228:231], v[68:71]
	v_mfma_f32_16x16x32_bf16 v[120:123], v[174:177], v[208:211], v[120:123]
	v_mfma_f32_16x16x32_bf16 v[112:115], v[182:185], v[208:211], v[112:115]
	v_mfma_f32_16x16x32_bf16 v[104:107], v[174:177], v[216:219], v[104:107]
	v_mfma_f32_16x16x32_bf16 v[96:99], v[182:185], v[216:219], v[96:99]
	v_mfma_f32_16x16x32_bf16 v[88:91], v[174:177], v[224:227], v[88:91]
	v_mfma_f32_16x16x32_bf16 v[80:83], v[182:185], v[224:227], v[80:83]
	v_mfma_f32_16x16x32_bf16 v[72:75], v[174:177], v[232:235], v[72:75]
	v_mfma_f32_16x16x32_bf16 v[68:71], v[182:185], v[232:235], v[68:71]
	s_setprio 0
	s_barrier
	s_add_i32 s18, s52, s28
	s_mov_b32 m0, s18
	ds_read_b128 v[186:189], v157 offset:16384
	ds_read_b128 v[208:211], v157 offset:17408
	ds_read_b128 v[212:215], v157 offset:18432
	ds_read_b128 v[216:219], v157 offset:19456
	ds_read_b128 v[220:223], v157 offset:20480
	ds_read_b128 v[224:227], v157 offset:21504
	ds_read_b128 v[228:231], v157 offset:22528
	ds_read_b128 v[232:235], v157 offset:23552
	global_load_lds_dwordx4 v2, s[22:23]
	s_add_i32 m0, s18, 0x2000
	s_add_u32 s18, s22, 0x10000
	s_addc_u32 s19, s23, 0
	s_add_i32 s52, s53, s28
	global_load_lds_dwordx4 v142, s[22:23]
	s_mov_b32 m0, s52
	s_nop 0
	global_load_lds_dwordx4 v2, s[18:19]
	s_add_i32 m0, s52, 0x2000
	s_nop 0
	global_load_lds_dwordx4 v142, s[18:19]
	s_mov_b32 m0, s29
	s_nop 0
	global_load_lds_dwordx4 v0, s[24:25]
	s_mov_b32 m0, s44
	s_nop 0
	global_load_lds_dwordx4 v140, s[24:25]
	s_waitcnt vmcnt(8)
	s_waitcnt lgkmcnt(0)
	s_barrier
	s_setprio 1
	v_mfma_f32_16x16x32_bf16 v[64:67], v[148:151], v[186:189], v[64:67]
	v_mfma_f32_16x16x32_bf16 v[60:63], v[162:165], v[186:189], v[60:63]
	v_mfma_f32_16x16x32_bf16 v[52:55], v[148:151], v[212:215], v[52:55]
	v_mfma_f32_16x16x32_bf16 v[44:47], v[162:165], v[212:215], v[44:47]
	v_mfma_f32_16x16x32_bf16 v[36:39], v[148:151], v[220:223], v[36:39]
	v_mfma_f32_16x16x32_bf16 v[28:31], v[162:165], v[220:223], v[28:31]
	v_mfma_f32_16x16x32_bf16 v[20:23], v[148:151], v[228:231], v[20:23]
	v_mfma_f32_16x16x32_bf16 v[12:15], v[162:165], v[228:231], v[12:15]
	v_mfma_f32_16x16x32_bf16 v[64:67], v[158:161], v[208:211], v[64:67]
	v_mfma_f32_16x16x32_bf16 v[60:63], v[166:169], v[208:211], v[60:63]
	v_mfma_f32_16x16x32_bf16 v[52:55], v[158:161], v[216:219], v[52:55]
	v_mfma_f32_16x16x32_bf16 v[44:47], v[166:169], v[216:219], v[44:47]
	v_mfma_f32_16x16x32_bf16 v[36:39], v[158:161], v[224:227], v[36:39]
	v_mfma_f32_16x16x32_bf16 v[28:31], v[166:169], v[224:227], v[28:31]
	v_mfma_f32_16x16x32_bf16 v[20:23], v[158:161], v[232:235], v[20:23]
	v_mfma_f32_16x16x32_bf16 v[12:15], v[166:169], v[232:235], v[12:15]
	s_setprio 0
	s_setprio 1
	v_mfma_f32_16x16x32_bf16 v[56:59], v[170:173], v[186:189], v[56:59]
	v_mfma_f32_16x16x32_bf16 v[48:51], v[178:181], v[186:189], v[48:51]
	v_mfma_f32_16x16x32_bf16 v[40:43], v[170:173], v[212:215], v[40:43]
	v_mfma_f32_16x16x32_bf16 v[32:35], v[178:181], v[212:215], v[32:35]
	v_mfma_f32_16x16x32_bf16 v[24:27], v[170:173], v[220:223], v[24:27]
	v_mfma_f32_16x16x32_bf16 v[16:19], v[178:181], v[220:223], v[16:19]
	v_mfma_f32_16x16x32_bf16 v[8:11], v[170:173], v[228:231], v[8:11]
	v_mfma_f32_16x16x32_bf16 v[4:7], v[178:181], v[228:231], v[4:7]
	v_mfma_f32_16x16x32_bf16 v[56:59], v[174:177], v[208:211], v[56:59]
	v_mfma_f32_16x16x32_bf16 v[48:51], v[182:185], v[208:211], v[48:51]
	v_mfma_f32_16x16x32_bf16 v[40:43], v[174:177], v[216:219], v[40:43]
	v_mfma_f32_16x16x32_bf16 v[32:35], v[182:185], v[216:219], v[32:35]
	v_mfma_f32_16x16x32_bf16 v[24:27], v[174:177], v[224:227], v[24:27]
	v_mfma_f32_16x16x32_bf16 v[16:19], v[182:185], v[224:227], v[16:19]
	v_mfma_f32_16x16x32_bf16 v[8:11], v[174:177], v[232:235], v[8:11]
	v_mfma_f32_16x16x32_bf16 v[4:7], v[182:185], v[232:235], v[4:7]
	s_setprio 0
	s_barrier
	s_add_i32 s52, 0, 0x18000
	s_add_i32 s53, 0, 0x1c000
	ds_read_b128 v[148:151], v246 offset:32768
	ds_read_b128 v[158:161], v246 offset:33792
	ds_read_b128 v[162:165], v246 offset:34816
	ds_read_b128 v[166:169], v246 offset:35840
	ds_read_b128 v[170:173], v246 offset:49152
	ds_read_b128 v[174:177], v246 offset:50176
	ds_read_b128 v[178:181], v246 offset:51200
	ds_read_b128 v[182:185], v246 offset:52224
	s_add_u32 s18, s24, 0x40000
	s_addc_u32 s19, s25, 0
	s_mov_b32 m0, s45
	ds_read_b128 v[186:189], v157 offset:32768
	ds_read_b128 v[208:211], v157 offset:33792
	ds_read_b128 v[212:215], v157 offset:34816
	ds_read_b128 v[216:219], v157 offset:35840
	ds_read_b128 v[220:223], v157 offset:36864
	ds_read_b128 v[224:227], v157 offset:37888
	ds_read_b128 v[228:231], v157 offset:38912
	ds_read_b128 v[232:235], v157 offset:39936
	global_load_lds_dwordx4 v0, s[18:19]
	s_mov_b32 m0, s46
	s_nop 0
	global_load_lds_dwordx4 v140, s[18:19]
	s_waitcnt vmcnt(8)
	s_waitcnt lgkmcnt(0)
	s_barrier
	s_setprio 1
	v_mfma_f32_16x16x32_bf16 v[128:131], v[148:151], v[186:189], v[128:131]
	v_mfma_f32_16x16x32_bf16 v[124:127], v[162:165], v[186:189], v[124:127]
	v_mfma_f32_16x16x32_bf16 v[116:119], v[148:151], v[212:215], v[116:119]
	v_mfma_f32_16x16x32_bf16 v[108:111], v[162:165], v[212:215], v[108:111]
	v_mfma_f32_16x16x32_bf16 v[100:103], v[148:151], v[220:223], v[100:103]
	v_mfma_f32_16x16x32_bf16 v[92:95], v[162:165], v[220:223], v[92:95]
	v_mfma_f32_16x16x32_bf16 v[84:87], v[148:151], v[228:231], v[84:87]
	v_mfma_f32_16x16x32_bf16 v[76:79], v[162:165], v[228:231], v[76:79]
	v_mfma_f32_16x16x32_bf16 v[128:131], v[158:161], v[208:211], v[128:131]
	v_mfma_f32_16x16x32_bf16 v[124:127], v[166:169], v[208:211], v[124:127]
	v_mfma_f32_16x16x32_bf16 v[116:119], v[158:161], v[216:219], v[116:119]
	v_mfma_f32_16x16x32_bf16 v[108:111], v[166:169], v[216:219], v[108:111]
	v_mfma_f32_16x16x32_bf16 v[100:103], v[158:161], v[224:227], v[100:103]
	v_mfma_f32_16x16x32_bf16 v[92:95], v[166:169], v[224:227], v[92:95]
	v_mfma_f32_16x16x32_bf16 v[84:87], v[158:161], v[232:235], v[84:87]
	v_mfma_f32_16x16x32_bf16 v[76:79], v[166:169], v[232:235], v[76:79]
	s_setprio 0
	s_setprio 1
	v_mfma_f32_16x16x32_bf16 v[120:123], v[170:173], v[186:189], v[120:123]
	v_mfma_f32_16x16x32_bf16 v[112:115], v[178:181], v[186:189], v[112:115]
	v_mfma_f32_16x16x32_bf16 v[104:107], v[170:173], v[212:215], v[104:107]
	v_mfma_f32_16x16x32_bf16 v[96:99], v[178:181], v[212:215], v[96:99]
	v_mfma_f32_16x16x32_bf16 v[88:91], v[170:173], v[220:223], v[88:91]
	v_mfma_f32_16x16x32_bf16 v[80:83], v[178:181], v[220:223], v[80:83]
	v_mfma_f32_16x16x32_bf16 v[72:75], v[170:173], v[228:231], v[72:75]
	v_mfma_f32_16x16x32_bf16 v[68:71], v[178:181], v[228:231], v[68:71]
	v_mfma_f32_16x16x32_bf16 v[120:123], v[174:177], v[208:211], v[120:123]
	v_mfma_f32_16x16x32_bf16 v[112:115], v[182:185], v[208:211], v[112:115]
	v_mfma_f32_16x16x32_bf16 v[104:107], v[174:177], v[216:219], v[104:107]
	v_mfma_f32_16x16x32_bf16 v[96:99], v[182:185], v[216:219], v[96:99]
	v_mfma_f32_16x16x32_bf16 v[88:91], v[174:177], v[224:227], v[88:91]
	v_mfma_f32_16x16x32_bf16 v[80:83], v[182:185], v[224:227], v[80:83]
	v_mfma_f32_16x16x32_bf16 v[72:75], v[174:177], v[232:235], v[72:75]
	v_mfma_f32_16x16x32_bf16 v[68:71], v[182:185], v[232:235], v[68:71]
	s_setprio 0
	s_barrier
	s_add_i32 s18, s52, s28
	s_add_u32 s100, s22, 0x80
	s_addc_u32 s101, s23, 0
	s_mov_b32 m0, s18
	ds_read_b128 v[186:189], v157 offset:49152
	ds_read_b128 v[208:211], v157 offset:50176
	ds_read_b128 v[212:215], v157 offset:51200
	ds_read_b128 v[216:219], v157 offset:52224
	ds_read_b128 v[220:223], v157 offset:53248
	ds_read_b128 v[224:227], v157 offset:54272
	ds_read_b128 v[228:231], v157 offset:55296
	ds_read_b128 v[232:235], v157 offset:56320
	global_load_lds_dwordx4 v2, s[100:101]
	s_add_i32 m0, s18, 0x2000
	s_add_u32 s18, s22, 0x10080
	s_addc_u32 s19, s23, 0
	s_add_i32 s22, s53, s28
	global_load_lds_dwordx4 v142, s[100:101]
	s_mov_b32 m0, s22
	s_nop 0
	global_load_lds_dwordx4 v2, s[18:19]
	s_add_i32 m0, s22, 0x2000
	s_nop 0
	global_load_lds_dwordx4 v142, s[18:19]
	s_add_u32 s100, s24, 0x80
	s_addc_u32 s101, s25, 0
	s_mov_b32 m0, s47
	s_nop 0
	global_load_lds_dwordx4 v0, s[100:101]
	s_mov_b32 m0, s48
	s_nop 0
	global_load_lds_dwordx4 v140, s[100:101]
	s_waitcnt vmcnt(8)
	s_waitcnt lgkmcnt(0)
	s_barrier
	s_setprio 1
	v_mfma_f32_16x16x32_bf16 v[64:67], v[148:151], v[186:189], v[64:67]
	v_mfma_f32_16x16x32_bf16 v[60:63], v[162:165], v[186:189], v[60:63]
	v_mfma_f32_16x16x32_bf16 v[52:55], v[148:151], v[212:215], v[52:55]
	v_mfma_f32_16x16x32_bf16 v[44:47], v[162:165], v[212:215], v[44:47]
	v_mfma_f32_16x16x32_bf16 v[36:39], v[148:151], v[220:223], v[36:39]
	v_mfma_f32_16x16x32_bf16 v[28:31], v[162:165], v[220:223], v[28:31]
	v_mfma_f32_16x16x32_bf16 v[20:23], v[148:151], v[228:231], v[20:23]
	v_mfma_f32_16x16x32_bf16 v[12:15], v[162:165], v[228:231], v[12:15]
	v_mfma_f32_16x16x32_bf16 v[64:67], v[158:161], v[208:211], v[64:67]
	v_mfma_f32_16x16x32_bf16 v[60:63], v[166:169], v[208:211], v[60:63]
	v_mfma_f32_16x16x32_bf16 v[52:55], v[158:161], v[216:219], v[52:55]
	v_mfma_f32_16x16x32_bf16 v[44:47], v[166:169], v[216:219], v[44:47]
	v_mfma_f32_16x16x32_bf16 v[36:39], v[158:161], v[224:227], v[36:39]
	v_mfma_f32_16x16x32_bf16 v[28:31], v[166:169], v[224:227], v[28:31]
	v_mfma_f32_16x16x32_bf16 v[20:23], v[158:161], v[232:235], v[20:23]
	v_mfma_f32_16x16x32_bf16 v[12:15], v[166:169], v[232:235], v[12:15]
	s_setprio 0
	s_setprio 1
	v_mfma_f32_16x16x32_bf16 v[56:59], v[170:173], v[186:189], v[56:59]
	v_mfma_f32_16x16x32_bf16 v[48:51], v[178:181], v[186:189], v[48:51]
	v_mfma_f32_16x16x32_bf16 v[40:43], v[170:173], v[212:215], v[40:43]
	v_mfma_f32_16x16x32_bf16 v[32:35], v[178:181], v[212:215], v[32:35]
	v_mfma_f32_16x16x32_bf16 v[24:27], v[170:173], v[220:223], v[24:27]
	v_mfma_f32_16x16x32_bf16 v[16:19], v[178:181], v[220:223], v[16:19]
	v_mfma_f32_16x16x32_bf16 v[8:11], v[170:173], v[228:231], v[8:11]
	v_mfma_f32_16x16x32_bf16 v[4:7], v[178:181], v[228:231], v[4:7]
	v_mfma_f32_16x16x32_bf16 v[56:59], v[174:177], v[208:211], v[56:59]
	v_mfma_f32_16x16x32_bf16 v[48:51], v[182:185], v[208:211], v[48:51]
	v_mfma_f32_16x16x32_bf16 v[40:43], v[174:177], v[216:219], v[40:43]
	v_mfma_f32_16x16x32_bf16 v[32:35], v[182:185], v[216:219], v[32:35]
	v_mfma_f32_16x16x32_bf16 v[24:27], v[174:177], v[224:227], v[24:27]
	v_mfma_f32_16x16x32_bf16 v[16:19], v[182:185], v[224:227], v[16:19]
	v_mfma_f32_16x16x32_bf16 v[8:11], v[174:177], v[232:235], v[8:11]
	v_mfma_f32_16x16x32_bf16 v[4:7], v[182:185], v[232:235], v[4:7]
	s_setprio 0
	s_barrier
	s_add_i32 s51, s51, 2
	s_add_u32 s40, s40, 0x100
	s_addc_u32 s41, s41, 0
	s_add_u32 s42, s42, 0x100
	s_addc_u32 s43, s43, 0
	s_cmp_gt_u32 s51, 13
	s_cbranch_scc0 .LBB0_928
	s_lshl_b32 s5, s16, 8
	s_and_b64 vcc, exec, s[2:3]
	s_cbranch_vccz .LBB0_931
	v_or_b32_e32 v148, s5, v154
	v_ashrrev_i32_e32 v149, 31, v148
	v_lshlrev_b64 v[148:149], 6, v[148:149]
	v_lshl_add_u64 v[166:167], s[74:75], 0, v[148:149]
	global_load_dwordx4 v[148:151], v[166:167], off
	global_load_dwordx4 v[158:161], v[166:167], off offset:32
	global_load_dwordx4 v[162:165], v[166:167], off offset:16
	s_nop 0
	global_load_dwordx4 v[166:169], v[166:167], off offset:48
	s_barrier
